# SSD chunk state update: 8 fragment reads hoisted into free VGPR quads (on top of v37)
# speedup vs baseline: 1.0106x; 1.0106x over previous
.LBB0_643:
	s_or_b64 exec, exec, s[14:15]
	s_waitcnt lgkmcnt(5)
	v_mul_f32_e32 v78, v64, v68
	v_cvt_pk_bf16_f32 v64, v70, s0
	ds_write_b16 v69, v64 offset:33008
	ds_read_b32 v64, v73 offset:53004
	v_lshlrev_b32_e32 v71, 3, v129
	s_waitcnt lgkmcnt(5)
	v_mul_f32_e32 v79, v65, v76
	v_mul_f32_e32 v60, v60, v68
	s_waitcnt lgkmcnt(3)
	v_mul_f32_e32 v80, v66, v77
	s_waitcnt lgkmcnt(0)
	v_mul_f32_e32 v63, v63, v64
	v_mul_f32_e32 v81, v67, v64
	v_lshl_add_u32 v64, v71, 1, 16
	v_mad_u32_u24 v65, v126, s54, v64
	s_barrier
	ds_read_b128 v[66:69], v65 offset:32768
	v_mul_f32_e32 v61, v61, v76
	v_mul_f32_e32 v62, v62, v77
	v_mad_u64_u32 v[76:77], s[14:15], v182, s54, v[64:65]
	ds_read_b128 v[70:73], v76 offset:27648
	s_waitcnt lgkmcnt(0)
	v_mfma_f32_16x16x32_bf16 v[60:63], v[66:69], v[70:73], v[60:63]
	ds_read_b128 v[70:73], v76 offset:28928
	s_sub_i32 s46, s79, 32
	s_add_i32 s47, s71, 32
	s_and_b64 s[14:15], s[12:13], exec
	s_cselect_b32 s46, s46, s47
	s_add_i32 s14, s46, s66
	s_waitcnt lgkmcnt(0)
	v_mfma_f32_16x16x32_bf16 v[66:69], v[66:69], v[70:73], v[78:81]
	v_lshl_add_u64 v[70:71], s[44:45], 0, v[0:1]
	v_mov_b32_e32 v0, s14
	v_mad_i32_i24 v72, v74, s67, v0
	v_ashrrev_i32_e32 v73, 31, v72
	v_lshlrev_b64 v[74:75], 12, v[72:73]
	v_ashrrev_i32_e32 v129, 31, v128
	v_lshl_add_u64 v[74:75], v[70:71], 0, v[74:75]
	v_lshlrev_b64 v[76:77], 1, v[128:129]
	v_cvt_pk_bf16_f32 v0, v60, s0
	v_lshl_add_u64 v[74:75], v[74:75], 0, v[76:77]
	v_add_u32_e32 v72, s67, v72
	global_store_short v[74:75], v0, off
	v_cvt_pk_bf16_f32 v0, v66, s0
	v_ashrrev_i32_e32 v73, 31, v72
	global_store_short v[74:75], v0, off offset:32
	v_lshlrev_b64 v[74:75], 12, v[72:73]
	v_lshl_add_u64 v[74:75], v[70:71], 0, v[74:75]
	v_cvt_pk_bf16_f32 v0, v61, s0
	v_lshl_add_u64 v[60:61], v[74:75], 0, v[76:77]
	global_store_short v[60:61], v0, off
	v_cvt_pk_bf16_f32 v0, v67, s0
	global_store_short v[60:61], v0, off offset:32
	v_add_u32_e32 v60, s67, v72
	v_ashrrev_i32_e32 v61, 31, v60
	v_lshlrev_b64 v[66:67], 12, v[60:61]
	v_add_u32_e32 v60, s67, v60
	v_lshl_add_u64 v[66:67], v[70:71], 0, v[66:67]
	v_ashrrev_i32_e32 v61, 31, v60
	v_cvt_pk_bf16_f32 v0, v62, s0
	v_lshl_add_u64 v[66:67], v[66:67], 0, v[76:77]
	v_lshlrev_b64 v[60:61], 12, v[60:61]
	global_store_short v[66:67], v0, off
	v_cvt_pk_bf16_f32 v0, v68, s0
	v_lshl_add_u64 v[60:61], v[70:71], 0, v[60:61]
	global_store_short v[66:67], v0, off offset:32
	v_cvt_pk_bf16_f32 v0, v63, s0
	v_lshl_add_u64 v[60:61], v[60:61], 0, v[76:77]
	global_store_short v[60:61], v0, off
	v_cvt_pk_bf16_f32 v0, v69, s0
	global_store_short v[60:61], v0, off offset:32
	v_or_b32_e32 v60, v177, v176
	v_mad_u64_u32 v[60:61], s[14:15], v60, s54, v[64:65]
	ds_read_b128 v[60:63], v60 offset:27648
	ds_read_b32 v0, v163 offset:53248
	v_mad_u32_u24 v68, v176, s54, v64
	ds_read_b128 v[64:67], v68 offset:17408
	ds_read_b128 v[208:211], v68 offset:18688
	ds_read_b128 v[212:215], v68 offset:19968
	ds_read_b128 v[216:219], v68 offset:21248
	ds_read_b128 v[220:223], v68 offset:22528
	ds_read_b128 v[224:227], v68 offset:23808
	ds_read_b128 v[228:231], v68 offset:25088
	ds_read_b128 v[232:235], v68 offset:26368
	s_add_i32 s79, s79, 32
	s_sub_i32 s71, s71, 32
	s_waitcnt lgkmcnt(8)
	v_pk_mul_f32 v[6:7], v[6:7], v[0:1] op_sel_hi:[1,0]
	v_pk_mul_f32 v[4:5], v[4:5], v[0:1] op_sel_hi:[1,0]
	v_pk_mul_f32 v[14:15], v[14:15], v[0:1] op_sel_hi:[1,0]
	v_pk_mul_f32 v[12:13], v[12:13], v[0:1] op_sel_hi:[1,0]
	s_waitcnt lgkmcnt(7)
	v_mfma_f32_16x16x32_bf16 v[4:7], v[60:63], v[64:67], v[4:7]
	v_pk_mul_f32 v[10:11], v[10:11], v[0:1] op_sel_hi:[1,0]
	v_pk_mul_f32 v[8:9], v[8:9], v[0:1] op_sel_hi:[1,0]
	s_waitcnt lgkmcnt(6)
	v_mfma_f32_16x16x32_bf16 v[12:15], v[60:63], v[208:211], v[12:15]
	v_pk_mul_f32 v[30:31], v[30:31], v[0:1] op_sel_hi:[1,0]
	v_pk_mul_f32 v[28:29], v[28:29], v[0:1] op_sel_hi:[1,0]
	s_waitcnt lgkmcnt(5)
	v_mfma_f32_16x16x32_bf16 v[8:11], v[60:63], v[212:215], v[8:11]
	v_pk_mul_f32 v[26:27], v[26:27], v[0:1] op_sel_hi:[1,0]
	v_pk_mul_f32 v[24:25], v[24:25], v[0:1] op_sel_hi:[1,0]
	s_waitcnt lgkmcnt(4)
	v_mfma_f32_16x16x32_bf16 v[28:31], v[60:63], v[216:219], v[28:31]
	v_pk_mul_f32 v[22:23], v[22:23], v[0:1] op_sel_hi:[1,0]
	v_pk_mul_f32 v[20:21], v[20:21], v[0:1] op_sel_hi:[1,0]
	s_waitcnt lgkmcnt(3)
	v_mfma_f32_16x16x32_bf16 v[24:27], v[60:63], v[220:223], v[24:27]
	v_pk_mul_f32 v[34:35], v[34:35], v[0:1] op_sel_hi:[1,0]
	v_pk_mul_f32 v[32:33], v[32:33], v[0:1] op_sel_hi:[1,0]
	s_waitcnt lgkmcnt(2)
	v_mfma_f32_16x16x32_bf16 v[20:23], v[60:63], v[224:227], v[20:23]
	v_pk_mul_f32 v[18:19], v[18:19], v[0:1] op_sel_hi:[1,0]
	v_pk_mul_f32 v[16:17], v[16:17], v[0:1] op_sel_hi:[1,0]
	s_waitcnt lgkmcnt(1)
	v_mfma_f32_16x16x32_bf16 v[32:35], v[60:63], v[228:231], v[32:35]
	s_cmp_eq_u32 s69, s78
	s_waitcnt lgkmcnt(0)
	v_mfma_f32_16x16x32_bf16 v[16:19], v[60:63], v[232:235], v[16:19]
	s_cbranch_scc1 .LBB0_695
